# SB phase: next unit's Q/gate loads issued after the unit's first step barrier (Q via v218-233), late-step barrier skips vmcnt, first-step barrier leaves the 4 epilogue stores in flight
# baseline (speedup 1.0000x reference)
; #define GAS __attribute__((address_space(1)))
; __host__ __device__ __forceinline__ size_t bl512(size_t row, int col) { return ((row >> 5) * 64 + (size_t)(col >> 3)) * 256 + (row & 31) * 8 + (col & 7); }
; #define SB_DMA(base_, kt_, slot) do { const GAS f16* b_ = (base_) + (size_t)(kt_) * 64 * KVW; const unsigned kd_ = (unsigned)__builtin_amdgcn_readfirstlane(kdst + (slot)), vd_ = (unsigned)__builtin_amdgcn_readfirstlane(vdst + (slot)); \
;         _Pragma("unroll") for (int i_ = 0; i_ < 4; ++i_) { glds16(b_ + koff[i_], kd_ + i_ * 1024); glds16(b_ + voff[i_], vd_ + i_ * 1024); } } while (0)
; __device__ __forceinline__ void sb_phase(LAS unsigned char* lds, const GAS f16* __restrict__ kv, const GAS f16* __restrict__ qg, GAS f16* __restrict__ mixed, int vcu, int G, unsigned long long& sw_acc) {
;     ...
;     const GAS f16* tbase = kv + ((size_t)U.b * SEQ) * KVW + U.hg * 256;
;     h8 qn[4]; u32x4 gn[4];
;     { const size_t grow = (size_t)U.b * SEQ + U.cq * 64 + 32 * rgp + l31; const int h = 4 * U.hg + hh;
;       const GAS f16* Qg = qg + S_SBQ * QG_SEC + bl512(grow, h * 64 + 8 * hi); const GAS f16* Gp = qg + S_SBG * QG_SEC + bl512(grow, h * 64);
; #pragma unroll
;       for (int d0 = 0; d0 < 4; ++d0) qn[d0] = *(const GAS h8*)(Qg + 512 * d0);
;       ld_groups_raw_bl(Gp, hi, gn); }
;     asm volatile("" : "+v"(qn[0]), "+v"(qn[1]), "+v"(qn[2]), "+v"(qn[3]));
;     SB_DMA(tbase, U.cq, islot); islot ^= SB_SLOT;
.LBB0_534:
	v_readlane_b32 s6, v250, 0
	v_readlane_b32 s7, v250, 1
	s_add_u32 s27, s6, 0x14000000
	s_addc_u32 s22, s7, 0
	s_ashr_i32 s6, s1, 8
	s_lshl_b32 s0, s6, 1
	s_add_i32 s0, s0, s4
	s_lshl_b32 s5, s4, 12
	s_and_b32 s0, s0, 3
	s_add_i32 s23, s5, 0
	s_lshl_b32 s11, s6, 5
	s_lshl_b32 s5, s0, 3
	s_lshl_b32 s7, s0, 1
	s_add_i32 s10, s23, 0x8000
	s_ashr_i32 s14, s11, 31
	v_readlane_b32 s15, v251, 15
	s_add_u32 s18, s15, s11
	v_readlane_b32 s15, v251, 16
	v_lshlrev_b32_e32 v2, 2, v4
	v_lshrrev_b32_e32 v5, 1, v4
	s_addc_u32 s19, s15, s14
	s_lshl_b32 s15, s0, 6
	v_readlane_b32 s20, v251, 13
	v_and_b32_e32 v2, 16, v2
	v_and_b32_e32 v12, 3, v4
	v_and_b32_e32 v5, 12, v5
	s_or_b32 s0, s20, s15
	v_bfe_u32 v11, v4, 5, 1
	v_or3_b32 v8, v12, v2, v5
	v_or_b32_e32 v2, s18, v4
	s_lshl_b64 s[18:19], s[18:19], 1
	s_lshr_b32 s0, s0, 3
	s_and_b32 s19, s19, 0xffffff
	s_andn2_b32 s18, s18, 63
	v_or_b32_e32 v6, s0, v11
	v_or_b32_e32 v6, s18, v6
	v_mov_b32_e32 v7, s19
	v_lshlrev_b64 v[6:7], 9, v[6:7]
	v_lshlrev_b32_e32 v2, 4, v2
	v_lshl_add_u64 v[6:7], s[82:83], 0, v[6:7]
	v_and_b32_e32 v2, 0x1f0, v2
	v_lshl_add_u64 v[6:7], v[6:7], 0, v[2:3]
	global_load_dwordx4 v[64:67], v[6:7], off offset:3072
	global_load_dwordx4 v[60:63], v[6:7], off offset:2048
	global_load_dwordx4 v[56:59], v[6:7], off offset:1024
	global_load_dwordx4 v[52:55], v[6:7], off
	v_or_b32_e32 v5, v5, v12
	v_lshlrev_b32_e32 v6, 9, v8
	v_or_b32_e32 v7, s5, v11
	v_bitop3_b32 v8, s5, v5, v11 bitop3:0x36
	v_lshl_or_b32 v117, v8, 4, v6
	v_bitop3_b32 v8, v7, v5, 2 bitop3:0x36
	v_lshl_or_b32 v135, v8, 4, v6
	v_bitop3_b32 v8, v7, v5, 4 bitop3:0x36
	v_bitop3_b32 v5, v7, v5, 6 bitop3:0x36
	s_or_b32 s18, s18, s0
	v_lshl_or_b32 v152, v8, 4, v6
	v_lshl_or_b32 v153, v5, 4, v6
	v_bfe_u32 v6, v4, 2, 2
	s_lshl_b64 s[18:19], s[18:19], 9
	v_lshlrev_b32_e32 v7, 9, v6
	v_lshlrev_b32_e32 v8, 1, v4
	v_lshlrev_b32_e32 v9, 3, v4
	s_add_u32 s18, s27, s18
	v_lshl_or_b32 v7, v11, 13, v7
	v_and_b32_e32 v8, 32, v8
	v_and_b32_e32 v9, 24, v9
	s_addc_u32 s19, s22, s19
	v_or3_b32 v13, v7, v8, v9
	v_lshl_add_u64 v[8:9], s[18:19], 0, v[2:3]
	v_lshlrev_b32_e32 v2, 9, v11
	v_lshl_add_u64 v[8:9], v[8:9], 0, v[2:3]
	global_load_dwordx4 v[68:71], v[8:9], off
	global_load_dwordx4 v[72:75], v[8:9], off offset:1024
	global_load_dwordx4 v[76:79], v[8:9], off offset:2048
	global_load_dwordx4 v[80:83], v[8:9], off offset:3072
	v_bitop3_b32 v15, s7, v6, 1 bitop3:0x36
	v_lshl_or_b32 v6, s4, 3, v11
	v_and_b32_e32 v116, 31, v4
	v_lshrrev_b32_e32 v5, 2, v4
	v_ashrrev_i32_e32 v7, 31, v6
	v_bitop3_b32 v14, s7, v5, 3 bitop3:0x78
	v_lshlrev_b64 v[118:119], 11, v[6:7]
	v_bitop3_b32 v5, v6, v116, 9 bitop3:0x6c
	v_lshl_or_b32 v120, v5, 3, v118
	v_lshlrev_b32_e32 v5, 2, v11
	v_and_b32_e32 v10, 63, v4
	v_and_b32_e32 v16, 28, v4
	v_bitop3_b32 v4, v5, v4, 28 bitop3:0x78
	v_or_b32_e32 v4, v4, v12
	v_lshlrev_b32_e32 v7, 3, v4
	v_or_b32_e32 v4, 2, v6
	v_readlane_b32 s0, v251, 8
	v_ashrrev_i32_e32 v5, 31, v4
	v_lshlrev_b32_e32 v2, 2, v4
	s_add_u32 s0, s8, s0
	v_lshlrev_b64 v[122:123], 11, v[4:5]
	v_bitop3_b32 v5, v4, v116, 11 bitop3:0x6c
	v_bitop3_b32 v2, v2, v16, 12 bitop3:0x6c
	v_or_b32_e32 v4, 4, v6
	s_addc_u32 s5, s9, 0
	s_lshl_b32 s7, s20, 1
	v_lshl_or_b32 v124, v5, 3, v122
	v_or_b32_e32 v2, v2, v12
	v_ashrrev_i32_e32 v5, 31, v4
	s_add_u32 s49, s0, s7
	v_lshl_or_b32 v122, v2, 3, v122
	v_lshlrev_b64 v[126:127], 11, v[4:5]
	v_bitop3_b32 v2, v4, v116, 13 bitop3:0x6c
	v_or_b32_e32 v4, 6, v6
	s_addc_u32 s0, s5, 0
	v_readlane_b32 s18, v251, 19
	v_ashrrev_i32_e32 v5, 31, v4
	v_readlane_b32 s19, v251, 20
	s_add_u32 s18, s49, s18
	v_mov_b32_e32 v121, v119
	v_lshl_or_b32 v128, v2, 3, v126
	v_lshlrev_b64 v[130:131], 11, v[4:5]
	v_bitop3_b32 v2, v4, v116, 15 bitop3:0x6c
	s_addc_u32 s19, s0, s19
	v_or_b32_e32 v118, v118, v7
	v_lshl_or_b32 v132, v2, 3, v130
	v_lshlrev_b32_e32 v2, 2, v4
	v_lshl_add_u64 v[4:5], v[120:121], 1, s[18:19]
	s_waitcnt vmcnt(4)
	s_mov_b32 s5, m0
	s_mov_b32 m0, s23
	s_nop 0
	global_load_lds_dwordx4 v[4:5], off
	s_mov_b32 m0, s5
	v_lshl_add_u64 v[4:5], v[118:119], 1, s[18:19]
	v_mov_b32_e32 v125, v123
	v_lshl_add_u64 v[4:5], v[4:5], 0, s[2:3]
	s_mov_b32 s5, m0
	s_mov_b32 m0, s10
	s_nop 0
	global_load_lds_dwordx4 v[4:5], off
	s_mov_b32 m0, s5
	v_lshl_add_u64 v[4:5], v[124:125], 1, s[18:19]
	s_add_i32 s5, s23, 0x400
	s_mov_b32 s7, m0
	s_mov_b32 m0, s5
	s_nop 0
	global_load_lds_dwordx4 v[4:5], off
	s_mov_b32 m0, s7
	v_lshl_add_u64 v[4:5], v[122:123], 1, s[18:19]
	v_mov_b32_e32 v129, v127
	v_lshl_add_u64 v[4:5], v[4:5], 0, s[2:3]
	s_add_i32 s5, s10, 0x400
	v_or_b32_e32 v126, v126, v7
	s_mov_b32 s7, m0
	s_mov_b32 m0, s5
	s_nop 0
	global_load_lds_dwordx4 v[4:5], off
	s_mov_b32 m0, s7
	v_lshl_add_u64 v[4:5], v[128:129], 1, s[18:19]
	s_add_i32 s5, s23, 0x800
	v_bitop3_b32 v2, v2, v16, 12 bitop3:0x6c
	s_mov_b32 s7, m0
	s_mov_b32 m0, s5
	s_nop 0
	global_load_lds_dwordx4 v[4:5], off
	s_mov_b32 m0, s7
	v_lshl_add_u64 v[4:5], v[126:127], 1, s[18:19]
	s_add_i32 s5, s10, 0x800
	s_lshl_b32 s4, s4, 2
	v_mov_b32_e32 v133, v131
	v_or_b32_e32 v2, v2, v12
	v_lshl_add_u64 v[4:5], v[4:5], 0, s[2:3]
	s_mov_b32 s7, m0
	s_mov_b32 m0, s5
	s_nop 0
	global_load_lds_dwordx4 v[4:5], off
	s_mov_b32 m0, s7
	s_add_i32 s5, s23, 0xc00
	s_add_i32 s48, s4, 0
	v_lshl_or_b32 v130, v2, 3, v130
	v_lshl_add_u64 v[4:5], v[132:133], 1, s[18:19]
	s_mov_b32 s7, m0
	s_mov_b32 m0, s5
	s_nop 0
	global_load_lds_dwordx4 v[4:5], off
	s_mov_b32 m0, s7
	s_add_i32 s5, s10, 0xc00
	s_add_i32 s48, s48, 0x24800
	v_lshl_add_u64 v[4:5], v[130:131], 1, s[18:19]
	s_cmp_eq_u32 s6, 1
	v_lshl_add_u64 v[4:5], v[4:5], 0, s[2:3]
	s_mov_b32 s7, m0
	s_mov_b32 m0, s5
	s_nop 0
	global_load_lds_dwordx4 v[4:5], off
	s_mov_b32 m0, s7
	s_cselect_b64 s[4:5], -1, 0
	s_cmp_lg_u32 s6, 1
	v_readlane_b32 s18, v251, 17
	s_cselect_b64 s[6:7], -1, 0
	s_cmpk_gt_u32 s1, 0xff
	s_mov_b32 s29, s18
	v_readlane_b32 s18, v251, 14
	v_lshlrev_b32_e32 v154, 3, v11
	v_lshlrev_b32_e32 v134, 8, v11
	s_cselect_b64 s[20:21], -1, 0
	v_lshlrev_b32_e32 v155, 4, v11
	v_cmp_gt_u32_e64 s[38:39], 32, v10
	s_mov_b32 s76, 0
	v_cmp_eq_u32_e64 s[40:41], 0, v10
	v_lshl_or_b32 v156, v14, 6, v13
	v_lshl_or_b32 v157, v15, 6, v13
	s_mov_b32 s50, 0x10000
	v_readlane_b32 s1, v251, 12
	s_mov_b32 s28, s18
	v_readlane_b32 s19, v251, 18
	s_waitcnt vmcnt(0)
	s_branch .LBB0_537

; #define SW_BEGIN(id) unsigned long long sw_t0_##id = 0; if (SW_ID == (id)) sw_t0_##id = __builtin_amdgcn_s_memrealtime()
; __device__ __forceinline__ void sb_phase(LAS unsigned char* lds, const GAS f16* __restrict__ kv, const GAS f16* __restrict__ qg, GAS f16* __restrict__ mixed, int vcu, int G, unsigned long long& sw_acc) {
;     ...
;         const size_t rowbase = (size_t)U.b * SEQ;
;         const int qw = U.cq * 64 + 32 * rgp, t = qw + l31, NT = U.cq + 1, h = 4 * U.hg + hh;
;         const size_t grow = rowbase + qw + l31;
;         h8 qr[4]; u32x4 gr[4];
; #pragma unroll
;         for (int d0 = 0; d0 < 4; ++d0) qr[d0] = qn[d0];
; #pragma unroll
;         for (int i = 0; i < 4; ++i) gr[i] = gn[i];
;         asm volatile("" : "+v"(gr[0]), "+v"(gr[1]), "+v"(gr[2]), "+v"(gr[3]));
;         const bool has_next = sb_decode(ui + G, Un);
;         f32x16 o[2]; o[0] = f32x16{}; o[1] = f32x16{};
;         float carry = 1.f; int done = 0;
;         bool spec = false, late = false; int nslot = 0;
;         const GAS f16* tbn = has_next ? kv + ((size_t)Un.b * SEQ) * KVW + Un.hg * 256 : tbase;
;         SW_BEGIN(12);
;         for (int j = 0; j < NT; ++j) {
;             SW_BEGIN(13);
;             WAIT_BAR(0);
;             SW_END(13);
;             if (j > 0) {
;                 const u32x4 f0 = *(const LAS u32x4*)(flags + ((j - 1) & 1) * 8), f1 = *(const LAS u32x4*)(flags + ((j - 1) & 1) * 8 + 4);
;                 const unsigned any = (f0.x | f0.y | f0.z | f0.w) | (f1.x | f1.y | f1.z | f1.w);
;                 if (!__builtin_amdgcn_readfirstlane(any)) break;
;             }
;             if (late) {
;                 SB_DMA(tbase, U.cq - j, cslot);
;                 WAIT_BAR(0);
;             } else if (has_next && (j + 1 == NT || j == SB_SPEC_J)) {
;                 SB_DMA(tbn, Un.cq, islot); nslot = islot; spec = true; late = true;
;             } else if (j + 1 < NT) { SB_DMA(tbase, U.cq - (j + 1), islot); islot ^= SB_SLOT; }
;     ...
;             const size_t grown = (size_t)Un.b * SEQ + Un.cq * 64 + 32 * rgp + l31; const int hn = 4 * Un.hg + hh;
;             const GAS f16* Qg = qg + S_SBQ * QG_SEC + bl512(grown, hn * 64 + 8 * hi); const GAS f16* Gp = qg + S_SBG * QG_SEC + bl512(grown, hn * 64);
; #pragma unroll
;             for (int d0 = 0; d0 < 4; ++d0) qn[d0] = *(const GAS h8*)(Qg + 512 * d0);
;             ld_groups_raw_bl(Gp, hi, gn);
.LBB0_537:
	s_add_i32 s79, s79, s90
	s_cmpk_lt_i32 s79, 0x400
	s_cselect_b64 s[34:35], -1, 0
	s_cmpk_gt_i32 s79, 0x3ff
	s_waitcnt vmcnt(8)
	v_mov_b64_e32 v[94:95], v[74:75]
	v_mov_b64_e32 v[86:87], v[82:83]
	v_mov_b64_e32 v[98:99], v[70:71]
	v_mov_b64_e32 v[90:91], v[78:79]
	s_cselect_b64 s[24:25], -1, 0
	v_mov_b64_e32 v[92:93], v[72:73]
	v_mov_b64_e32 v[84:85], v[80:81]
	v_mov_b64_e32 v[96:97], v[68:69]
	v_mov_b64_e32 v[88:89], v[76:77]
	s_and_b64 vcc, exec, s[24:25]
	s_cbranch_vccnz .LBB0_539
	s_ashr_i32 s19, s79, 5
	s_bfe_u32 s18, s79, 0x30001
	s_and_b32 s19, s19, -8
	s_bfe_u32 s30, s79, 0x40004
	s_and_b32 s84, s79, 1
	s_or_b32 s18, s18, s19
.LBB0_539:
	s_lshl_b32 s51, s29, 6
	s_add_i32 s85, s51, s11
	s_cmp_lt_i32 s29, 0
	s_mov_b32 s53, 0
	s_cbranch_scc1 .LBB0_553
	s_ashr_i32 s31, s30, 31
	s_lshl_b64 s[36:37], s[30:31], 23
	s_add_u32 s19, s8, s36
	s_addc_u32 s31, s9, s37
	s_lshl_b32 s36, s84, 8
	s_ashr_i32 s37, s36, 31
	s_lshl_b64 s[36:37], s[36:37], 1
	s_add_u32 s19, s19, s36
	s_addc_u32 s31, s31, s37
	s_and_b64 s[36:37], s[34:35], exec
	s_cselect_b32 s31, s31, s0
	s_cselect_b32 s42, s19, s49
	s_ashr_i32 s19, s18, 31
	s_lshl_b64 s[36:37], s[18:19], 18
	s_add_u32 s44, s42, s36
	s_addc_u32 s45, s31, s37
	s_cmp_lg_u32 s29, 0
	s_cselect_b64 s[42:43], -1, 0
	s_cmp_eq_u32 s29, 0
	s_waitcnt vmcnt(4) lgkmcnt(0)
	s_barrier
	s_cselect_b64 s[36:37], -1, 0
	s_andn2_b64 vcc, exec, s[34:35]
	s_cbranch_vccnz .Lsb_pf_skip
	s_ashr_i32 s47, s30, 31
	s_mov_b32 s46, s30
	s_lshl_b64 s[46:47], s[46:47], 11
	s_lshl_b32 s19, s18, 6
	s_ashr_i32 s31, s19, 31
	s_add_u32 s19, s19, s11
	s_addc_u32 s31, s31, s14
	s_add_u32 s46, s19, s46
	s_addc_u32 s47, s31, s47
	s_lshl_b32 s19, s84, 8
	s_or_b32 s19, s19, s15
	v_or_b32_e32 v236, s19, v154
	v_or_b32_e32 v238, s46, v116
	s_lshl_b64 s[46:47], s[46:47], 1
	v_ashrrev_i32_e32 v234, 3, v236
	s_ashr_i32 s19, s19, 3
	s_and_b32 s47, s47, 0xffffff
	s_andn2_b32 s46, s46, 63
	v_ashrrev_i32_e32 v235, 31, v234
	s_ashr_i32 s31, s19, 31
	v_lshl_add_u64 v[234:235], s[46:47], 0, v[234:235]
	s_add_u32 s46, s46, s19
	s_addc_u32 s47, s47, s31
	v_lshlrev_b64 v[234:235], 9, v[234:235]
	v_lshlrev_b32_e32 v238, 4, v238
	s_lshl_b64 s[46:47], s[46:47], 9
	v_lshl_add_u64 v[234:235], s[82:83], 0, v[234:235]
	v_and_b32_e32 v238, 0x1f0, v238
	v_mov_b32_e32 v239, 0
	s_add_u32 s46, s27, s46
	v_lshl_add_u64 v[234:235], v[234:235], 0, v[238:239]
	s_addc_u32 s47, s22, s47
	global_load_dwordx4 v[218:221], v[234:235], off
	global_load_dwordx4 v[222:225], v[234:235], off offset:1024
	global_load_dwordx4 v[226:229], v[234:235], off offset:2048
	global_load_dwordx4 v[230:233], v[234:235], off offset:3072
	v_lshl_add_u64 v[236:237], s[46:47], 0, v[238:239]
	v_lshlrev_b32_e32 v240, 1, v134
	v_mov_b32_e32 v241, 0
	v_lshl_add_u64 v[236:237], v[236:237], 0, v[240:241]
	global_load_dwordx4 v[68:71], v[236:237], off
	global_load_dwordx4 v[72:75], v[236:237], off offset:1024
	global_load_dwordx4 v[76:79], v[236:237], off offset:2048
	global_load_dwordx4 v[80:83], v[236:237], off offset:3072
.Lsb_pf_skip:
	s_and_b64 s[36:37], s[34:35], s[36:37]
	v_cndmask_b32_e64 v2, 0, 1, s[42:43]
	s_mov_b64 s[46:47], -1
	s_and_b64 vcc, exec, s[36:37]
	v_cmp_ne_u32_e64 s[42:43], 1, v2
	s_cbranch_vccnz .LBB0_544
	s_and_b64 vcc, exec, s[42:43]
	s_mov_b32 s19, s50
	s_cbranch_vccnz .LBB0_543
	s_add_i32 s80, s29, -1
	s_lshl_b64 s[46:47], s[80:81], 18
	s_add_u32 s46, s49, s46
	s_addc_u32 s47, s0, s47
	v_lshl_add_u64 v[4:5], v[120:121], 1, s[46:47]
	s_add_i32 s19, s50, s23
	s_mov_b32 s52, m0
	s_mov_b32 m0, s19
	s_nop 0
	global_load_lds_dwordx4 v[4:5], off
	s_mov_b32 m0, s52
	v_lshl_add_u64 v[4:5], v[118:119], 1, s[46:47]
	v_lshl_add_u64 v[4:5], v[4:5], 0, s[2:3]
	s_add_i32 s31, s50, s10
	s_mov_b32 s52, m0
	s_mov_b32 m0, s31
	s_nop 0
	global_load_lds_dwordx4 v[4:5], off
	s_mov_b32 m0, s52
	v_lshl_add_u64 v[4:5], v[124:125], 1, s[46:47]
	s_add_i32 s52, s19, 0x400
	s_mov_b32 s53, m0
	s_mov_b32 m0, s52
	s_nop 0
	global_load_lds_dwordx4 v[4:5], off
	s_mov_b32 m0, s53
	v_lshl_add_u64 v[4:5], v[122:123], 1, s[46:47]
	v_lshl_add_u64 v[4:5], v[4:5], 0, s[2:3]
	s_add_i32 s52, s31, 0x400
	s_mov_b32 s53, m0
	s_mov_b32 m0, s52
	s_nop 0
	global_load_lds_dwordx4 v[4:5], off
	s_mov_b32 m0, s53
	v_lshl_add_u64 v[4:5], v[128:129], 1, s[46:47]
	s_add_i32 s52, s19, 0x800
	s_mov_b32 s53, m0
	s_mov_b32 m0, s52
	s_nop 0
	global_load_lds_dwordx4 v[4:5], off
	s_mov_b32 m0, s53
	v_lshl_add_u64 v[4:5], v[126:127], 1, s[46:47]
	v_lshl_add_u64 v[4:5], v[4:5], 0, s[2:3]
	s_add_i32 s52, s31, 0x800
	s_mov_b32 s53, m0
	s_mov_b32 m0, s52
	s_nop 0
	global_load_lds_dwordx4 v[4:5], off
	s_mov_b32 m0, s53
	v_lshl_add_u64 v[4:5], v[132:133], 1, s[46:47]
	s_addk_i32 s19, 0xc00
	s_mov_b32 s52, m0
	s_mov_b32 m0, s19
	s_nop 0
	global_load_lds_dwordx4 v[4:5], off
	s_mov_b32 m0, s52
	v_lshl_add_u64 v[4:5], v[130:131], 1, s[46:47]
	v_lshl_add_u64 v[4:5], v[4:5], 0, s[2:3]
	s_add_i32 s19, s31, 0xc00
	s_mov_b32 s31, m0
	s_mov_b32 m0, s19
	s_nop 0
	global_load_lds_dwordx4 v[4:5], off
	s_mov_b32 m0, s31
	s_xor_b32 s19, s50, 0x10000

; #define GAS __attribute__((address_space(1)))
; __host__ __device__ __forceinline__ size_t bl512(size_t row, int col) { return ((row >> 5) * 64 + (size_t)(col >> 3)) * 256 + (row & 31) * 8 + (col & 7); }
; #define SB_DMA(base_, kt_, slot) do { const GAS f16* b_ = (base_) + (size_t)(kt_) * 64 * KVW; const unsigned kd_ = (unsigned)__builtin_amdgcn_readfirstlane(kdst + (slot)), vd_ = (unsigned)__builtin_amdgcn_readfirstlane(vdst + (slot)); \
;         _Pragma("unroll") for (int i_ = 0; i_ < 4; ++i_) { glds16(b_ + koff[i_], kd_ + i_ * 1024); glds16(b_ + voff[i_], vd_ + i_ * 1024); } } while (0)
; __device__ __forceinline__ void sb_phase(LAS unsigned char* lds, const GAS f16* __restrict__ kv, const GAS f16* __restrict__ qg, GAS f16* __restrict__ mixed, int vcu, int G, unsigned long long& sw_acc) {
;     ...
;         if (spec) { cslot = nslot; islot = nslot ^ SB_SLOT; }
;         else cslot = islot;
;         if (has_next) {
;             const size_t grown = (size_t)Un.b * SEQ + Un.cq * 64 + 32 * rgp + l31; const int hn = 4 * Un.hg + hh;
;             const GAS f16* Qg = qg + S_SBQ * QG_SEC + bl512(grown, hn * 64 + 8 * hi); const GAS f16* Gp = qg + S_SBG * QG_SEC + bl512(grown, hn * 64);
; #pragma unroll
;             for (int d0 = 0; d0 < 4; ++d0) qn[d0] = *(const GAS h8*)(Qg + 512 * d0);
;             ld_groups_raw_bl(Gp, hi, gn);
;             asm volatile("" ::: "memory");
;             tbase = kv + ((size_t)Un.b * SEQ) * KVW + Un.hg * 256;
;             if (!spec) { SB_DMA(tbase, Un.cq, islot); islot ^= SB_SLOT; }
;         }
.LBB0_554:
	s_xor_b32 s29, s53, 0x10000
	s_and_b64 s[36:37], s[42:43], exec
	s_cselect_b32 s19, s29, s50
	s_andn2_b64 vcc, exec, s[34:35]
	v_lshlrev_b32_e32 v36, 1, v134
	s_nop 15
	s_nop 7
	s_cbranch_vccnz .LBB0_536
	s_ashr_i32 s31, s30, 31
	s_xor_b64 s[34:35], s[42:43], -1
	s_lshl_b32 s44, s84, 8
	s_waitcnt vmcnt(8)
	v_mov_b64_e32 v[52:53], v[218:219]
	v_mov_b64_e32 v[54:55], v[220:221]
	v_mov_b64_e32 v[56:57], v[222:223]
	v_mov_b64_e32 v[58:59], v[224:225]
	v_mov_b64_e32 v[60:61], v[226:227]
	v_mov_b64_e32 v[62:63], v[228:229]
	v_mov_b64_e32 v[64:65], v[230:231]
	v_mov_b64_e32 v[66:67], v[232:233]
	s_lshl_b64 s[36:37], s[30:31], 23
	s_add_u32 s0, s8, s36
	s_addc_u32 s19, s9, s37
	s_ashr_i32 s45, s44, 31
	s_lshl_b64 s[36:37], s[44:45], 1
	s_add_u32 s49, s0, s36
	s_addc_u32 s0, s19, s37
	s_andn2_b64 vcc, exec, s[34:35]
	s_cbranch_vccnz .LBB0_535
	s_ashr_i32 s19, s18, 31
	s_lshl_b64 s[34:35], s[18:19], 18
	s_add_u32 s34, s49, s34
	s_addc_u32 s35, s0, s35
	v_lshl_add_u64 v[38:39], v[120:121], 1, s[34:35]
	s_add_i32 s19, s50, s23
	s_mov_b32 s31, m0
	s_mov_b32 m0, s19
	s_nop 0
	global_load_lds_dwordx4 v[38:39], off
	s_mov_b32 m0, s31
	v_lshl_add_u64 v[38:39], v[118:119], 1, s[34:35]
	v_lshl_add_u64 v[38:39], v[38:39], 0, s[2:3]
	s_add_i32 s29, s50, s10
	s_mov_b32 s31, m0
	s_mov_b32 m0, s29
	s_nop 0
	global_load_lds_dwordx4 v[38:39], off
	s_mov_b32 m0, s31
	v_lshl_add_u64 v[38:39], v[124:125], 1, s[34:35]
	s_add_i32 s31, s19, 0x400
	s_mov_b32 s36, m0
	s_mov_b32 m0, s31
	s_nop 0
	global_load_lds_dwordx4 v[38:39], off
	s_mov_b32 m0, s36
	v_lshl_add_u64 v[38:39], v[122:123], 1, s[34:35]
	v_lshl_add_u64 v[38:39], v[38:39], 0, s[2:3]
	s_add_i32 s31, s29, 0x400
	s_mov_b32 s36, m0
	s_mov_b32 m0, s31
	s_nop 0
	global_load_lds_dwordx4 v[38:39], off
	s_mov_b32 m0, s36
	v_lshl_add_u64 v[38:39], v[128:129], 1, s[34:35]
	s_add_i32 s31, s19, 0x800
	s_mov_b32 s36, m0
	s_mov_b32 m0, s31
	s_nop 0
	global_load_lds_dwordx4 v[38:39], off
	s_mov_b32 m0, s36
	v_lshl_add_u64 v[38:39], v[126:127], 1, s[34:35]
	v_lshl_add_u64 v[38:39], v[38:39], 0, s[2:3]
	s_add_i32 s31, s29, 0x800
	s_mov_b32 s36, m0
	s_mov_b32 m0, s31
	s_nop 0
	global_load_lds_dwordx4 v[38:39], off
	s_mov_b32 m0, s36
	v_lshl_add_u64 v[38:39], v[132:133], 1, s[34:35]
	s_addk_i32 s19, 0xc00
	s_mov_b32 s31, m0
	s_mov_b32 m0, s19
	s_nop 0
	global_load_lds_dwordx4 v[38:39], off
	s_mov_b32 m0, s31
	v_lshl_add_u64 v[38:39], v[130:131], 1, s[34:35]
	v_lshl_add_u64 v[38:39], v[38:39], 0, s[2:3]
	s_add_i32 s19, s29, 0xc00
	s_mov_b32 s29, m0
	s_mov_b32 m0, s19
	s_nop 0
	global_load_lds_dwordx4 v[38:39], off
	s_mov_b32 m0, s29
	s_xor_b32 s29, s50, 0x10000
	s_branch .LBB0_535

; #define SW_BEGIN(id) unsigned long long sw_t0_##id = 0; if (SW_ID == (id)) sw_t0_##id = __builtin_amdgcn_s_memrealtime()
; #define SW_END(id) do { if (SW_ID == (id)) sw_acc += __builtin_amdgcn_s_memrealtime() - sw_t0_##id; } while (0)
; #define SW_BEGIN(id) do {} while (0)
; #define SW_END(id) do {} while (0)
; #define LAS __attribute__((address_space(3)))
; #define WAIT_BAR(N) asm volatile("s_waitcnt vmcnt(" #N ") lgkmcnt(0)\n\ts_barrier" ::: "memory")
; #define SB_DMA(base_, kt_, slot) do { const GAS f16* b_ = (base_) + (size_t)(kt_) * 64 * KVW; const unsigned kd_ = (unsigned)__builtin_amdgcn_readfirstlane(kdst + (slot)), vd_ = (unsigned)__builtin_amdgcn_readfirstlane(vdst + (slot)); \
;         _Pragma("unroll") for (int i_ = 0; i_ < 4; ++i_) { glds16(b_ + koff[i_], kd_ + i_ * 1024); glds16(b_ + voff[i_], vd_ + i_ * 1024); } } while (0)
; __device__ __forceinline__ void sb_phase(LAS unsigned char* lds, const GAS f16* __restrict__ kv, const GAS f16* __restrict__ qg, GAS f16* __restrict__ mixed, int vcu, int G, unsigned long long& sw_acc) {
;     ...
;         for (int j = 0; j < NT; ++j) {
;             SW_BEGIN(13);
;             WAIT_BAR(0);
;             SW_END(13);
;             if (j > 0) {
;                 const u32x4 f0 = *(const LAS u32x4*)(flags + ((j - 1) & 1) * 8), f1 = *(const LAS u32x4*)(flags + ((j - 1) & 1) * 8 + 4);
;                 const unsigned any = (f0.x | f0.y | f0.z | f0.w) | (f1.x | f1.y | f1.z | f1.w);
;                 if (!__builtin_amdgcn_readfirstlane(any)) break;
;             }
;             if (late) {
;                 SB_DMA(tbase, U.cq - j, cslot);
;                 WAIT_BAR(0);
;             } else if (has_next && (j + 1 == NT || j == SB_SPEC_J)) {
;                 SB_DMA(tbn, Un.cq, islot); nslot = islot; spec = true; late = true;
;             } else if (j + 1 < NT) { SB_DMA(tbase, U.cq - (j + 1), islot); islot ^= SB_SLOT; }
.LBB0_565:
	s_and_b32 s56, s54, 8
	s_xor_b32 s42, s56, 8
	s_lshl_b32 s42, s42, 2
	s_add_i32 s42, s42, 0
	s_add_i32 s42, s42, 0x24800
	s_and_b64 vcc, exec, s[44:45]
	s_cbranch_vccnz .Lsb_top_late
	s_waitcnt vmcnt(0)
.Lsb_top_late:
	s_waitcnt lgkmcnt(0)
	s_barrier
	v_mov_b32_e32 v2, s42
	ds_read_b128 v[36:39], v2
	ds_read_b128 v[40:43], v2 offset:16
	s_mov_b64 s[46:47], -1
	s_waitcnt lgkmcnt(1)
	v_or_b32_e32 v2, v36, v37
	v_or_b32_e32 v2, v2, v38
	v_or_b32_e32 v2, v2, v39
	s_waitcnt lgkmcnt(0)
	v_or_b32_e32 v2, v2, v41
	v_or_b32_e32 v2, v2, v40
	v_or_b32_e32 v2, v2, v42
	v_or_b32_e32 v2, v2, v43
	s_nop 0
	v_readfirstlane_b32 s42, v2
	s_cmp_eq_u32 s42, 0
	s_cbranch_scc1 .LBB0_583
	s_xor_b64 s[42:43], s[44:45], -1
	s_add_i32 s58, s29, s52
	s_and_b64 vcc, exec, s[42:43]
	s_cbranch_vccz .LBB0_575
	s_mov_b64 s[42:43], 0
	s_andn2_b64 vcc, exec, s[34:35]
	s_mov_b64 s[44:45], s[24:25]
	s_cbranch_vccnz .LBB0_569
	s_cmp_lg_u32 s58, 2
	s_cselect_b64 s[42:43], -1, 0
	s_cmp_lg_u32 s52, 0
	s_cselect_b64 s[44:45], -1, 0
	s_and_b64 s[44:45], s[42:43], s[44:45]
	s_mov_b64 s[42:43], -1
